# grid-barrier arrival invalidate of non-leader workgroups narrowed to the vector L1 (buffer_inv sc0): the XCD leader still invalidates the L2 after its write-back, early arrivers no longer drop the L2
# speedup vs baseline: 1.0068x; 1.0068x over previous
; __device__ __forceinline__ unsigned xb_ld(unsigned* p)              { return __hip_atomic_load(p, __ATOMIC_RELAXED, __HIP_MEMORY_SCOPE_AGENT); }
; __device__ __forceinline__ unsigned xb_add(unsigned* p, unsigned v) { return __hip_atomic_fetch_add(p, v, __ATOMIC_RELAXED, __HIP_MEMORY_SCOPE_AGENT); }
; #define XB_SPIN(cond, bar) do { unsigned _sp = 0; while (cond) { __builtin_amdgcn_s_sleep(1); \
;     if ((++_sp & 255u) == 0u) { if (xb_ld(&(bar)[XB_TMO])) break; if (_sp > XB_SPIN_CAP) { atomicAdd(&(bar)[XB_TMO], 1u); break; } } } } while (0)
; __device__ __forceinline__ void xcd_barrier(const XcdBarrier& b) {
;     asm volatile("s_waitcnt vmcnt(0)" ::: "memory");
;     __syncthreads();
;     if (threadIdx.x == 0) {
;         unsigned* bar = b.bar;
;         __builtin_amdgcn_s_waitcnt(0);
;         unsigned nloc = b.st[0], nx = b.st[1];
;         if (nloc == 0u) { xcd_barrier_complete(bar, b.x, nloc, nx); b.st[0] = nloc; b.st[1] = nx; }
;         const unsigned old = xb_add(&bar[XB_XSUB(b.x)], 1u);
;         const unsigned gen = old / nloc;
;         if (old + 1u == (gen + 1u) * nloc) {
;             __builtin_amdgcn_fence(__ATOMIC_RELEASE, "agent");
;             asm volatile("s_waitcnt vmcnt(0)" ::: "memory");
;             const unsigned og = xb_add(&bar[XB_TOP], 1u);
;             const unsigned tg = og / nx;
;             if (og + 1u == (tg + 1u) * nx) xb_add(&bar[XB_TOPGEN], 1u);
;             else XB_SPIN(xb_ld(&bar[XB_TOPGEN]) == tg, bar);
;             __builtin_amdgcn_fence(__ATOMIC_ACQUIRE, "agent");
;             xb_add(&bar[XB_XGEN(b.x)], 1u);
;             asm volatile("s_waitcnt vmcnt(0)" ::: "memory");
;         } else {
;             XB_SPIN(xb_ld(&bar[XB_XGEN(b.x)]) == gen, bar);
;             __builtin_amdgcn_fence(__ATOMIC_ACQUIRE, "agent");
;             asm volatile("s_waitcnt vmcnt(0)" ::: "memory");
;         }
.LBB0_279:
	v_readlane_b32 s0, v255, 4
	s_lshl_b32 s22, s33, 6
	v_readlane_b32 s1, v255, 5
	s_mov_b32 s5, s1
	s_add_i32 s4, s22, 0x500
	v_writelane_b32 v255, s0, 4
	v_mov_b32_e32 v1, 1
	s_nop 0
	v_writelane_b32 v255, s1, 5
	s_lshl_b64 s[0:1], s[4:5], 2
	s_add_u32 s0, s34, s0
	s_addc_u32 s1, s35, s1
	v_mov_b64_e32 v[4:5], s[0:1]
	flat_atomic_add v3, v[4:5], v1 sc0
	v_cvt_f32_u32_e32 v1, v2
	v_sub_u32_e32 v4, 0, v2
	v_rcp_iflag_f32_e32 v1, v1
	s_nop 0
	v_mul_f32_e32 v1, 0x4f7ffffe, v1
	v_cvt_u32_f32_e32 v1, v1
	v_mul_lo_u32 v4, v4, v1
	v_mul_hi_u32 v4, v1, v4
	v_add_u32_e32 v1, v1, v4
	s_waitcnt vmcnt(0) lgkmcnt(0)
	v_mul_hi_u32 v1, v3, v1
	v_mul_lo_u32 v4, v1, v2
	v_sub_u32_e32 v4, v3, v4
	v_cmp_ge_u32_e32 vcc, v4, v2
	v_add_u32_e32 v5, 1, v1
	s_nop 0
	v_cndmask_b32_e32 v1, v1, v5, vcc
	v_sub_u32_e32 v5, v4, v2
	v_cndmask_b32_e32 v4, v4, v5, vcc
	v_cmp_ge_u32_e32 vcc, v4, v2
	v_add_u32_e32 v4, 1, v1
	s_nop 0
	v_cndmask_b32_e32 v1, v1, v4, vcc
	v_add_u32_e32 v4, 1, v3
	v_mad_u64_u32 v[2:3], s[0:1], v2, v1, v[2:3]
	v_cmp_ne_u32_e32 vcc, v4, v2
	s_and_saveexec_b64 s[0:1], vcc
	s_xor_b64 s[0:1], exec, s[0:1]
	s_cbranch_execz .LBB0_292
	buffer_inv sc0
	v_readlane_b32 s4, v255, 4
	v_readlane_b32 s5, v255, 5
	s_mov_b32 s7, s5
	s_add_i32 s6, s22, 0x900
	v_writelane_b32 v255, s4, 4
	s_nop 1
	v_writelane_b32 v255, s5, 5
	s_lshl_b64 s[4:5], s[6:7], 2
	s_add_u32 s6, s34, s4
	s_addc_u32 s7, s35, s5
	v_mov_b64_e32 v[2:3], s[6:7]
	flat_load_dword v0, v[2:3] sc1
	s_waitcnt vmcnt(0) lgkmcnt(0)
	v_cmp_eq_u32_e32 vcc, v0, v1
	s_and_saveexec_b64 s[4:5], vcc
	s_cbranch_execz .LBB0_291
	s_mov_b32 s23, 1
	s_mov_b64 s[8:9], 0
	s_branch .LBB0_283

; __device__ __forceinline__ unsigned xb_ld(unsigned* p)              { return __hip_atomic_load(p, __ATOMIC_RELAXED, __HIP_MEMORY_SCOPE_AGENT); }
; __device__ __forceinline__ unsigned xb_add(unsigned* p, unsigned v) { return __hip_atomic_fetch_add(p, v, __ATOMIC_RELAXED, __HIP_MEMORY_SCOPE_AGENT); }
; #define XB_SPIN(cond, bar) do { unsigned _sp = 0; while (cond) { __builtin_amdgcn_s_sleep(1); \
;     if ((++_sp & 255u) == 0u) { if (xb_ld(&(bar)[XB_TMO])) break; if (_sp > XB_SPIN_CAP) { atomicAdd(&(bar)[XB_TMO], 1u); break; } } } } while (0)
; __device__ __forceinline__ void xcd_barrier(const XcdBarrier& b) {
;     ...
;         const unsigned old = xb_add(&bar[XB_XSUB(b.x)], 1u);
;         const unsigned gen = old / nloc;
;         if (old + 1u == (gen + 1u) * nloc) {
;             __builtin_amdgcn_fence(__ATOMIC_RELEASE, "agent");
;             asm volatile("s_waitcnt vmcnt(0)" ::: "memory");
;             const unsigned og = xb_add(&bar[XB_TOP], 1u);
;             const unsigned tg = og / nx;
;             if (og + 1u == (tg + 1u) * nx) xb_add(&bar[XB_TOPGEN], 1u);
;             else XB_SPIN(xb_ld(&bar[XB_TOPGEN]) == tg, bar);
;             __builtin_amdgcn_fence(__ATOMIC_ACQUIRE, "agent");
;             xb_add(&bar[XB_XGEN(b.x)], 1u);
;             asm volatile("s_waitcnt vmcnt(0)" ::: "memory");
;         } else {
;             XB_SPIN(xb_ld(&bar[XB_XGEN(b.x)]) == gen, bar);
;             __builtin_amdgcn_fence(__ATOMIC_ACQUIRE, "agent");
;             asm volatile("s_waitcnt vmcnt(0)" ::: "memory");
;         }
.LBB0_669:
	v_readlane_b32 s0, v255, 4
	s_lshl_b32 s20, s33, 6
	v_readlane_b32 s1, v255, 5
	s_mov_b32 s3, s1
	s_add_i32 s2, s20, 0x500
	v_writelane_b32 v255, s0, 4
	v_mov_b32_e32 v1, 1
	s_nop 0
	v_writelane_b32 v255, s1, 5
	s_lshl_b64 s[0:1], s[2:3], 2
	s_add_u32 s0, s34, s0
	s_addc_u32 s1, s35, s1
	v_mov_b64_e32 v[4:5], s[0:1]
	flat_atomic_add v3, v[4:5], v1 sc0
	v_cvt_f32_u32_e32 v1, v2
	v_sub_u32_e32 v4, 0, v2
	v_rcp_iflag_f32_e32 v1, v1
	s_nop 0
	v_mul_f32_e32 v1, 0x4f7ffffe, v1
	v_cvt_u32_f32_e32 v1, v1
	v_mul_lo_u32 v4, v4, v1
	v_mul_hi_u32 v4, v1, v4
	v_add_u32_e32 v1, v1, v4
	s_waitcnt vmcnt(0) lgkmcnt(0)
	v_mul_hi_u32 v1, v3, v1
	v_mul_lo_u32 v4, v1, v2
	v_sub_u32_e32 v4, v3, v4
	v_cmp_ge_u32_e32 vcc, v4, v2
	v_add_u32_e32 v5, 1, v1
	s_nop 0
	v_cndmask_b32_e32 v1, v1, v5, vcc
	v_sub_u32_e32 v5, v4, v2
	v_cndmask_b32_e32 v4, v4, v5, vcc
	v_cmp_ge_u32_e32 vcc, v4, v2
	v_add_u32_e32 v4, 1, v1
	s_nop 0
	v_cndmask_b32_e32 v1, v1, v4, vcc
	v_add_u32_e32 v4, 1, v3
	v_mad_u64_u32 v[2:3], s[0:1], v2, v1, v[2:3]
	v_cmp_ne_u32_e32 vcc, v4, v2
	s_and_saveexec_b64 s[0:1], vcc
	s_xor_b64 s[0:1], exec, s[0:1]
	s_cbranch_execz .LBB0_682
	buffer_inv sc0
	v_readlane_b32 s2, v255, 4
	v_readlane_b32 s3, v255, 5
	s_mov_b32 s5, s3
	s_add_i32 s4, s20, 0x900
	v_writelane_b32 v255, s2, 4
	s_nop 1
	v_writelane_b32 v255, s3, 5
	s_lshl_b64 s[2:3], s[4:5], 2
	s_add_u32 s4, s34, s2
	s_addc_u32 s5, s35, s3
	v_mov_b64_e32 v[2:3], s[4:5]
	flat_load_dword v0, v[2:3] sc1
	s_waitcnt vmcnt(0) lgkmcnt(0)
	v_cmp_eq_u32_e32 vcc, v0, v1
	s_and_saveexec_b64 s[2:3], vcc
	s_cbranch_execz .LBB0_681
	s_mov_b32 s21, 1
	s_mov_b64 s[6:7], 0
	s_branch .LBB0_673

; __device__ __forceinline__ unsigned xb_ld(unsigned* p)              { return __hip_atomic_load(p, __ATOMIC_RELAXED, __HIP_MEMORY_SCOPE_AGENT); }
; __device__ __forceinline__ unsigned xb_add(unsigned* p, unsigned v) { return __hip_atomic_fetch_add(p, v, __ATOMIC_RELAXED, __HIP_MEMORY_SCOPE_AGENT); }
; #define XB_SPIN(cond, bar) do { unsigned _sp = 0; while (cond) { __builtin_amdgcn_s_sleep(1); \
;     if ((++_sp & 255u) == 0u) { if (xb_ld(&(bar)[XB_TMO])) break; if (_sp > XB_SPIN_CAP) { atomicAdd(&(bar)[XB_TMO], 1u); break; } } } } while (0)
; __device__ __forceinline__ void xcd_barrier(const XcdBarrier& b) {
;     ...
;         const unsigned old = xb_add(&bar[XB_XSUB(b.x)], 1u);
;         const unsigned gen = old / nloc;
;         if (old + 1u == (gen + 1u) * nloc) {
;             __builtin_amdgcn_fence(__ATOMIC_RELEASE, "agent");
;             asm volatile("s_waitcnt vmcnt(0)" ::: "memory");
;             const unsigned og = xb_add(&bar[XB_TOP], 1u);
;             const unsigned tg = og / nx;
;             if (og + 1u == (tg + 1u) * nx) xb_add(&bar[XB_TOPGEN], 1u);
;             else XB_SPIN(xb_ld(&bar[XB_TOPGEN]) == tg, bar);
;             __builtin_amdgcn_fence(__ATOMIC_ACQUIRE, "agent");
;             xb_add(&bar[XB_XGEN(b.x)], 1u);
;             asm volatile("s_waitcnt vmcnt(0)" ::: "memory");
;         } else {
;             XB_SPIN(xb_ld(&bar[XB_XGEN(b.x)]) == gen, bar);
;             __builtin_amdgcn_fence(__ATOMIC_ACQUIRE, "agent");
;             asm volatile("s_waitcnt vmcnt(0)" ::: "memory");
;         }
.LBB0_828:
	v_readlane_b32 s0, v255, 4
	s_lshl_b32 s22, s33, 6
	v_readlane_b32 s1, v255, 5
	s_mov_b32 s3, s1
	s_add_i32 s2, s22, 0x500
	v_writelane_b32 v255, s0, 4
	v_mov_b32_e32 v1, 1
	s_nop 0
	v_writelane_b32 v255, s1, 5
	s_lshl_b64 s[0:1], s[2:3], 2
	s_add_u32 s0, s36, s0
	s_addc_u32 s1, s37, s1
	v_mov_b64_e32 v[4:5], s[0:1]
	flat_atomic_add v3, v[4:5], v1 sc0
	v_cvt_f32_u32_e32 v1, v2
	v_sub_u32_e32 v4, 0, v2
	v_rcp_iflag_f32_e32 v1, v1
	s_nop 0
	v_mul_f32_e32 v1, 0x4f7ffffe, v1
	v_cvt_u32_f32_e32 v1, v1
	v_mul_lo_u32 v4, v4, v1
	v_mul_hi_u32 v4, v1, v4
	v_add_u32_e32 v1, v1, v4
	s_waitcnt vmcnt(0) lgkmcnt(0)
	v_mul_hi_u32 v1, v3, v1
	v_mul_lo_u32 v4, v1, v2
	v_sub_u32_e32 v4, v3, v4
	v_cmp_ge_u32_e32 vcc, v4, v2
	v_add_u32_e32 v5, 1, v1
	s_nop 0
	v_cndmask_b32_e32 v1, v1, v5, vcc
	v_sub_u32_e32 v5, v4, v2
	v_cndmask_b32_e32 v4, v4, v5, vcc
	v_cmp_ge_u32_e32 vcc, v4, v2
	v_add_u32_e32 v4, 1, v1
	s_nop 0
	v_cndmask_b32_e32 v1, v1, v4, vcc
	v_add_u32_e32 v4, 1, v3
	v_mad_u64_u32 v[2:3], s[0:1], v2, v1, v[2:3]
	v_cmp_ne_u32_e32 vcc, v4, v2
	s_and_saveexec_b64 s[0:1], vcc
	s_xor_b64 s[0:1], exec, s[0:1]
	s_cbranch_execz .LBB0_841
	buffer_inv sc0
	v_readlane_b32 s2, v255, 4
	v_readlane_b32 s3, v255, 5
	s_mov_b32 s7, s3
	s_add_i32 s6, s22, 0x900
	v_writelane_b32 v255, s2, 4
	s_nop 1
	v_writelane_b32 v255, s3, 5
	s_lshl_b64 s[2:3], s[6:7], 2
	s_add_u32 s6, s36, s2
	s_addc_u32 s7, s37, s3
	v_mov_b64_e32 v[2:3], s[6:7]
	flat_load_dword v0, v[2:3] sc1
	s_waitcnt vmcnt(0) lgkmcnt(0)
	v_cmp_eq_u32_e32 vcc, v0, v1
	s_and_saveexec_b64 s[2:3], vcc
	s_cbranch_execz .LBB0_840
	s_mov_b32 s23, 1
	s_mov_b64 s[8:9], 0
	s_branch .LBB0_832
